# v9 + FFN1 meta rows folded into the gate|up GEMM as row panel 64 (86 extra units appended), meta skinny GEMM of P1 removed
# baseline (speedup 1.0000x reference)
.LBB0_118:
	s_or_b64 exec, exec, s[2:3]
	s_mov_b64 s[2:3], s[90:91]
	s_cmpk_gt_i32 s22, -1
	s_barrier
	v_mbcnt_lo_u32_b32 v1, -1, 0
	v_mbcnt_hi_u32_b32 v1, -1, v1
	s_cbranch_scc1 .LBB0_123
	s_load_dwordx2 s[4:5], s[2:3], 0xc8
	v_and_b32_e32 v2, 15, v1
	v_and_b32_e32 v0, -16, v1
	v_lshlrev_b32_e32 v3, 13, v2
	v_or_b32_e32 v68, 0x4000, v2
	s_waitcnt lgkmcnt(0)
	s_add_u32 s8, s4, 0x800000
	s_addc_u32 s9, s5, 0
	s_lshl_b32 s0, s81, 10
	s_lshl_b32 s10, s81, 11
	s_cmp_lt_u32 s61, 64
	v_lshl_add_u32 v70, v1, 4, 0
	v_add3_u32 v0, v0, s0, v3
	s_cselect_b64 s[2:3], -1, 0
	v_ashrrev_i32_e32 v1, 2, v1
	v_lshlrev_b32_e32 v2, 13, v68
	v_mov_b32_e32 v3, 0
	s_add_u32 s6, s4, 0x27600000
	v_and_b32_e32 v71, -4, v1
	v_mov_b32_e32 v1, v3
	s_waitcnt vmcnt(4)
	v_add_u32_e32 v4, 64, v0
	v_mov_b32_e32 v5, v3
	v_add_u32_e32 v6, 0x80, v0
	v_mov_b32_e32 v7, v3
	v_add_u32_e32 v8, 0xc0, v0
	v_mov_b32_e32 v9, v3
	v_add_u32_e32 v10, 0x100, v0
	v_mov_b32_e32 v11, v3
	v_add_u32_e32 v12, 0x140, v0
	v_mov_b32_e32 v13, v3
	v_add_u32_e32 v14, 0x180, v0
	v_mov_b32_e32 v15, v3
	v_add_u32_e32 v16, 0x1c0, v0
	v_mov_b32_e32 v17, v3
	v_add_u32_e32 v18, 0x200, v0
	v_mov_b32_e32 v19, v3
	v_add_u32_e32 v20, 0x240, v0
	v_mov_b32_e32 v21, v3
	v_add_u32_e32 v22, 0x280, v0
	v_mov_b32_e32 v23, v3
	v_add_u32_e32 v24, 0x2c0, v0
	v_mov_b32_e32 v25, v3
	v_add_u32_e32 v26, 0x300, v0
	v_mov_b32_e32 v27, v3
	v_add_u32_e32 v28, 0x340, v0
	v_mov_b32_e32 v29, v3
	v_add_u32_e32 v30, 0x380, v0
	v_mov_b32_e32 v31, v3
	v_add_u32_e32 v32, 0x3c0, v0
	v_mov_b32_e32 v33, v3
	s_addc_u32 s7, s5, 0
	v_lshl_add_u64 v[66:67], s[4:5], 0, v[2:3]
	v_lshlrev_b32_e32 v2, 2, v68
	v_lshl_add_u64 v[34:35], s[6:7], 0, v[0:1]
	v_lshl_add_u64 v[36:37], s[6:7], 0, v[4:5]
	v_lshl_add_u64 v[38:39], s[6:7], 0, v[6:7]
	v_lshl_add_u64 v[40:41], s[6:7], 0, v[8:9]
	v_lshl_add_u64 v[42:43], s[6:7], 0, v[10:11]
	v_lshl_add_u64 v[44:45], s[6:7], 0, v[12:13]
	v_lshl_add_u64 v[46:47], s[6:7], 0, v[14:15]
	v_lshl_add_u64 v[48:49], s[6:7], 0, v[16:17]
	v_lshl_add_u64 v[50:51], s[6:7], 0, v[18:19]
	v_lshl_add_u64 v[52:53], s[6:7], 0, v[20:21]
	v_lshl_add_u64 v[54:55], s[6:7], 0, v[22:23]
	v_lshl_add_u64 v[56:57], s[6:7], 0, v[24:25]
	v_lshl_add_u64 v[58:59], s[6:7], 0, v[26:27]
	v_lshl_add_u64 v[60:61], s[6:7], 0, v[28:29]
	v_lshl_add_u64 v[62:63], s[6:7], 0, v[30:31]
	v_lshl_add_u64 v[64:65], s[6:7], 0, v[32:33]
	s_mov_b64 s[6:7], 0x2fa00000
	v_lshl_add_u64 v[68:69], s[4:5], 0, v[2:3]
	s_mov_b64 s[4:5], 0x600000
	v_lshl_add_u64 v[66:67], v[66:67], 0, s[6:7]
	v_lshl_add_u64 v[68:69], v[68:69], 0, s[4:5]
	s_lshl_b32 s11, s22, 4
	s_lshl_b32 s12, s72, 4
	s_lshl_b32 s13, s22, 5
	s_lshl_b32 s14, s72, 5
	s_movk_i32 s15, 0x7fff
	s_mov_b32 s16, 0x8200000
	v_mov_b32_e32 v72, 1
	s_mov_b32 s17, s22
	global_load_dwordx4 v[4:7], v[34:35], off
	global_load_dwordx4 v[8:11], v[34:35], off offset:64
	global_load_dwordx4 v[12:15], v[34:35], off offset:128
	global_load_dwordx4 v[16:19], v[34:35], off offset:192
	global_load_dwordx4 v[20:23], v[34:35], off offset:256
	global_load_dwordx4 v[24:27], v[34:35], off offset:320
	global_load_dwordx4 v[28:31], v[34:35], off offset:384
	global_load_dwordx4 v[36:39], v[34:35], off offset:448
	global_load_dwordx4 v[40:43], v[34:35], off offset:512
	global_load_dwordx4 v[44:47], v[34:35], off offset:576
	global_load_dwordx4 v[48:51], v[34:35], off offset:640
	global_load_dwordx4 v[52:55], v[34:35], off offset:704
	global_load_dwordx4 v[56:59], v[34:35], off offset:768
	global_load_dwordx4 v[60:63], v[34:35], off offset:832
	global_load_dwordx4 v[246:249], v[34:35], off offset:896
	global_load_dwordx4 v[250:253], v[34:35], off offset:960
	s_branch .LBB0_121

.LBB0_128:
	s_add_u32 s44, s8, 0x2fa00000
	s_addc_u32 s45, s9, 0
	s_lshl_b32 s1, s11, 5
	s_mov_b64 s[8:9], 0x80
	s_and_b32 s1, s1, 0x60
	s_add_i32 m0, s29, 0x18000
	v_lshl_add_u64 v[6:7], v[6:7], 0, s[8:9]
	s_lshl_b32 s0, s12, 13
	s_lshl_b32 s11, s1, 7
	s_waitcnt vmcnt(2)
	s_barrier
	global_load_lds_dwordx4 v[6:7], off
	v_lshl_add_u64 v[4:5], v[4:5], 0, s[8:9]
	s_add_i32 m0, s29, 0x1a000
	s_add_i32 s46, s29, 0x8000
	s_add_i32 s47, s29, 0xa000
	global_load_lds_dwordx4 v[4:5], off
	v_lshl_add_u64 v[0:1], v[0:1], 0, s[8:9]
	s_mov_b32 m0, s46
	s_add_u32 s14, s36, 0x100080
	global_load_lds_dwordx4 v[0:1], off
	v_lshl_add_u64 v[0:1], v[2:3], 0, s[8:9]
	s_mov_b32 m0, s47
	s_addc_u32 s15, s37, 0
	global_load_lds_dwordx4 v[0:1], off
	s_add_i32 m0, s29, 0x1c000
	v_lshl_add_u64 v[0:1], s[14:15], 0, v[132:133]
	global_load_lds_dwordx4 v[0:1], off
	v_lshl_add_u64 v[0:1], s[14:15], 0, v[136:137]
	s_add_i32 m0, s29, 0x1e000
	s_cmpk_lt_u32 s10, 0x100
	global_load_lds_dwordx4 v[0:1], off
	v_lshrrev_b32_e32 v1, 1, v8
	v_and_b32_e32 v1, 24, v1
	v_and_b32_e32 v0, 15, v8
	v_lshlrev_b32_e32 v2, 1, v1
	v_lshl_or_b32 v152, s12, 6, v0
	v_lshl_or_b32 v2, v0, 6, v2
	v_lshlrev_b32_e32 v0, 2, v0
	v_and_b32_e32 v3, 32, v0
	v_bitop3_b32 v4, v2, s0, v3 bitop3:0xde
	v_bitop3_b32 v153, s11, v2, v3 bitop3:0xf6
	s_cselect_b64 s[10:11], -1, 0
	s_lshl_b32 s0, s12, 8
	s_add_i32 s0, s0, 0
	s_add_i32 s0, s0, 0x20000
	v_add_u32_e32 v154, s0, v0
	v_lshlrev_b32_e32 v0, 16, v9
	v_and_b32_e32 v0, 0xfffe0000, v0
	v_or_b32_e32 v155, s1, v1
	v_lshl_add_u32 v0, v10, 13, v0
	v_and_b32_e32 v1, 1, v9
	v_lshl_or_b32 v0, v1, 6, v0
	v_lshl_add_u32 v140, v11, 1, v0
	v_lshlrev_b32_e32 v0, 16, v12
	v_and_b32_e32 v0, 0xfffe0000, v0
	s_waitcnt vmcnt(6)
	v_lshl_add_u32 v0, v13, 13, v0
	v_and_b32_e32 v1, 1, v12
	v_lshl_or_b32 v0, v1, 6, v0
	s_add_i32 s51, 0, 0x10000
	s_add_i32 s52, 0, 0x14000
	s_mov_b32 s48, 0
	s_ashr_i32 s49, s72, 31
	v_lshl_add_u64 v[138:139], s[2:3], 0, v[128:129]
	v_mov_b32_e32 v141, v129
	v_lshl_add_u32 v142, v14, 1, v0
	v_mov_b32_e32 v143, v129
	v_mov_b64_e32 v[144:145], 0x15d6
	v_mov_b64_e32 v[146:147], 0x15d5
	s_movk_i32 s50, 0x2b1
	v_add_u32_e32 v156, s51, v153
	v_add_u32_e32 v157, s52, v153
	v_add_u32_e32 v158, 0, v4
	s_mov_b32 s53, 0x100000
	s_mov_b32 s54, 0x120000
	s_mov_b32 s55, 0x140000
	s_mov_b32 s56, 0
	s_barrier
	s_branch .LBB0_131

.LBB0_131:
	s_add_i32 s56, s56, 1
	s_mul_i32 s0, s56, s49
	s_mul_hi_u32 s1, s56, s72
	s_add_i32 s1, s1, s0
	s_mul_i32 s0, s56, s72
	s_add_u32 s18, s0, s22
	s_addc_u32 s19, s1, s23
	v_cmp_gt_i64_e32 vcc, s[18:19], v[146:147]
	v_cmp_lt_i64_e64 s[2:3], s[18:19], v[144:145]
	s_cbranch_vccnz .LBB0_133
	s_ashr_i32 s0, s18, 31
	s_lshr_b32 s0, s0, 29
	s_add_i32 s0, s18, s0
	s_ashr_i32 s1, s0, 3
	s_and_b32 s0, s0, -8
	s_sub_i32 s0, s18, s0
	s_mulk_i32 s0, 0x2b0
	s_add_i32 s0, s0, s1
	s_cmpk_ge_i32 s18, 0x1580
	s_cselect_b32 s0, s18, s0
	s_mul_hi_i32 s1, s0, 0x2fa0be83
	s_lshr_b32 s12, s1, 31
	s_ashr_i32 s1, s1, 7
	s_add_i32 s1, s1, s12
	s_lshl_b32 s12, s1, 3
	s_sub_i32 s13, 0x41, s12
	s_min_i32 s13, s13, 8
	s_abs_i32 s14, s13
	v_cvt_f32_u32_e32 v0, s14
	s_sub_i32 s16, 0, s14
	s_mulk_i32 s1, 0x2b0
	s_sub_i32 s0, s0, s1
	v_rcp_iflag_f32_e32 v0, v0
	s_abs_i32 s1, s0
	s_xor_b32 s15, s0, s13
	s_ashr_i32 s15, s15, 31
	v_mul_f32_e32 v0, 0x4f7ffffe, v0
	v_cvt_u32_f32_e32 v0, v0
	s_nop 0
	v_readfirstlane_b32 s17, v0
	s_mul_i32 s16, s16, s17
	s_mul_hi_u32 s16, s17, s16
	s_add_i32 s17, s17, s16
	s_mul_hi_u32 s16, s1, s17
	s_mul_i32 s17, s16, s14
	s_sub_i32 s1, s1, s17
	s_add_i32 s18, s16, 1
	s_sub_i32 s17, s1, s14
	s_cmp_ge_u32 s1, s14
	s_cselect_b32 s16, s18, s16
	s_cselect_b32 s1, s17, s1
	s_add_i32 s17, s16, 1
	s_cmp_ge_u32 s1, s14
	s_cselect_b32 s1, s17, s16
	s_xor_b32 s1, s1, s15
	s_sub_i32 s14, s1, s15
	s_mul_i32 s1, s14, s13
	s_sub_i32 s0, s0, s1
	s_add_i32 s16, s12, s0
